# combo5 + attention step B: LDS-DMA issue hoisted ahead of the row-max tree (replaces nop padding), canonicalising self-max ops dropped
# speedup vs baseline: 1.0056x; 1.0056x over previous
.LBB0_198:
	v_add_u32_e32 v0, s8, v206
	ds_read_b64_tr_b16 v[178:179], v0 offset:24576
	ds_read_b64_tr_b16 v[180:181], v0 offset:25088
	s_waitcnt lgkmcnt(9)
	v_mfma_f32_32x32x16_bf16 v[98:113], v[174:177], v[138:141], v[34:49]
	v_add_f32_e32 v82, v66, v67
	v_add_f32_e32 v82, v68, v82
	v_add_f32_e32 v82, v69, v82
	v_add_f32_e32 v82, v70, v82
	v_add_f32_e32 v82, v71, v82
	v_cvt_pk_bf16_f32 v142, v66, v67
	v_cvt_pk_bf16_f32 v143, v68, v69
	ds_read_b64_tr_b16 v[174:175], v0 offset:28672
	ds_read_b64_tr_b16 v[176:177], v0 offset:29184
	v_add_f32_e32 v66, v72, v82
	s_waitcnt lgkmcnt(10)
	v_mfma_f32_32x32x16_bf16 v[82:97], v[170:173], v[138:141], v[34:49]
	v_add_f32_e32 v66, v73, v66
	v_add_f32_e32 v66, v74, v66
	v_add_f32_e32 v122, v75, v66
	v_cvt_pk_bf16_f32 v144, v70, v71
	v_cvt_pk_bf16_f32 v145, v72, v73
	ds_read_b64_tr_b16 v[66:67], v0 offset:25600
	ds_read_b64_tr_b16 v[68:69], v0 offset:26112
	s_waitcnt lgkmcnt(11)
	v_mfma_f32_32x32x16_bf16 v[98:113], v[166:169], v[126:129], v[98:113]
	v_add_f32_e32 v70, v76, v122
	v_add_f32_e32 v70, v77, v70
	v_add_f32_e32 v70, v78, v70
	v_add_f32_e32 v122, v79, v70
	v_cvt_pk_bf16_f32 v134, v74, v75
	v_cvt_pk_bf16_f32 v135, v76, v77
	ds_read_b64_tr_b16 v[70:71], v0 offset:29696
	ds_read_b64_tr_b16 v[72:73], v0 offset:30208
	s_waitcnt lgkmcnt(12)
	v_mfma_f32_32x32x16_bf16 v[82:97], v[162:165], v[126:129], v[82:97]
	v_add_f32_e32 v74, v80, v122
	v_add_f32_e32 v74, v81, v74
	v_add_f32_e32 v74, v50, v74
	v_add_f32_e32 v122, v51, v74
	v_cvt_pk_bf16_f32 v136, v78, v79
	v_cvt_pk_bf16_f32 v137, v80, v81
	ds_read_b64_tr_b16 v[74:75], v0 offset:26624
	ds_read_b64_tr_b16 v[76:77], v0 offset:27136
	s_waitcnt lgkmcnt(13)
	v_mfma_f32_32x32x16_bf16 v[98:113], v[158:161], v[118:121], v[98:113]
	v_add_f32_e32 v78, v52, v122
	v_add_f32_e32 v78, v53, v78
	v_add_f32_e32 v78, v54, v78
	v_add_f32_e32 v78, v55, v78
	v_cvt_pk_bf16_f32 v130, v50, v51
	v_cvt_pk_bf16_f32 v131, v52, v53
	ds_read_b64_tr_b16 v[50:51], v0 offset:30720
	ds_read_b64_tr_b16 v[52:53], v0 offset:31232
	s_waitcnt lgkmcnt(14)
	v_mfma_f32_32x32x16_bf16 v[82:97], v[154:157], v[118:121], v[82:97]
	v_add_f32_e32 v78, v56, v78
	v_add_f32_e32 v78, v57, v78
	v_add_f32_e32 v78, v58, v78
	v_add_f32_e32 v78, v59, v78
	v_cvt_pk_bf16_f32 v132, v54, v55
	v_cvt_pk_bf16_f32 v133, v56, v57
	ds_read_b64_tr_b16 v[54:55], v0 offset:27648
	ds_read_b64_tr_b16 v[56:57], v0 offset:28160
	s_waitcnt lgkmcnt(14)
	v_mfma_f32_32x32x16_bf16 v[98:113], v[150:153], v[114:117], v[98:113]
	v_add_f32_e32 v78, v60, v78
	v_add_f32_e32 v78, v61, v78
	v_add_f32_e32 v78, v62, v78
	v_add_f32_e32 v78, v63, v78
	v_cvt_pk_bf16_f32 v122, v58, v59
	v_cvt_pk_bf16_f32 v123, v60, v61
	ds_read_b64_tr_b16 v[58:59], v0 offset:31744
	ds_read_b64_tr_b16 v[60:61], v0 offset:32256
	v_mfma_f32_32x32x16_bf16 v[82:97], v[146:149], v[114:117], v[82:97]
	v_add_f32_e32 v0, v64, v78
	v_add_f32_e32 v0, v65, v0
	v_cvt_pk_bf16_f32 v124, v62, v63
	v_cvt_pk_bf16_f32 v125, v64, v65
	v_lshl_add_u64 v[62:63], v[184:185], 0, s[98:99]
	s_add_i32 s8, s21, s40
	s_mov_b32 m0, s8
	s_nop 0
	global_load_lds_dwordx4 v[62:63], off
	v_lshl_add_u64 v[62:63], v[182:183], 0, s[98:99]
	s_add_i32 s8, s18, s41
	s_mov_b32 m0, s8
	s_nop 0
	global_load_lds_dwordx4 v[62:63], off
	v_max_f32_e32 v62, v98, v99
	v_max3_f32 v63, v100, v101, v83
	v_max3_f32 v62, v62, v82, v84
	v_max3_f32 v62, v62, v85, v102
	v_max3_f32 v63, v63, v104, v105
	v_max3_f32 v62, v62, v103, v86
	v_max3_f32 v63, v63, v88, v89
	v_max3_f32 v62, v62, v87, v106
	v_max3_f32 v63, v63, v108, v109
	v_max3_f32 v62, v62, v107, v90
	v_max3_f32 v63, v63, v92, v93
	v_max3_f32 v62, v62, v91, v110
	v_max3_f32 v63, v63, v112, v113
	v_max3_f32 v62, v62, v111, v94
	v_max3_f32 v63, v63, v96, v97
	v_max3_f32 v62, v62, v95, v63
	v_mov_b32_e32 v63, v62
	s_nop 1
	v_permlane32_swap_b32_e32 v62, v63
	v_max_f32_e32 v62, v62, v63
	v_cmp_lt_f32_e32 vcc, s91, v62
	s_cmp_lg_u64 vcc, 0
	v_add_f32_e32 v0, v208, v0
	s_cselect_b64 s[8:9], -1, 0
	s_cbranch_vccnz .LBB0_206

.LBB0_201:
	s_add_i32 s8, s18, 0x2000
	s_cmpk_lg_i32 s18, 0x4000
	s_cselect_b32 s44, s8, 0
	v_add_u32_e32 v186, s21, v206
	ds_read_b64_tr_b16 v[150:151], v186 offset:24576
	ds_read_b64_tr_b16 v[152:153], v186 offset:25088
	s_waitcnt lgkmcnt(9)
	v_mfma_f32_32x32x16_bf16 v[66:81], v[62:65], v[138:141], v[34:49]
	v_add_f32_e32 v50, v98, v99
	v_add_f32_e32 v50, v100, v50
	v_add_f32_e32 v50, v101, v50
	v_add_f32_e32 v50, v102, v50
	v_add_f32_e32 v50, v103, v50
	v_cvt_pk_bf16_f32 v142, v98, v99
	v_cvt_pk_bf16_f32 v143, v100, v101
	ds_read_b64_tr_b16 v[146:147], v186 offset:28672
	ds_read_b64_tr_b16 v[148:149], v186 offset:29184
	v_add_f32_e32 v50, v104, v50
	v_add_f32_e32 v50, v105, v50
	v_add_f32_e32 v50, v106, v50
	v_add_f32_e32 v122, v107, v50
	s_waitcnt lgkmcnt(10)
	v_mfma_f32_32x32x16_bf16 v[50:65], v[174:177], v[138:141], v[34:49]
	v_cvt_pk_bf16_f32 v144, v102, v103
	v_cvt_pk_bf16_f32 v145, v104, v105
	ds_read_b64_tr_b16 v[98:99], v186 offset:25600
	ds_read_b64_tr_b16 v[100:101], v186 offset:26112
	s_waitcnt lgkmcnt(11)
	v_mfma_f32_32x32x16_bf16 v[66:81], v[178:181], v[126:129], v[66:81]
	v_add_f32_e32 v102, v108, v122
	v_add_f32_e32 v102, v109, v102
	v_add_f32_e32 v102, v110, v102
	v_add_f32_e32 v122, v111, v102
	v_cvt_pk_bf16_f32 v134, v106, v107
	v_cvt_pk_bf16_f32 v135, v108, v109
	ds_read_b64_tr_b16 v[102:103], v186 offset:29696
	ds_read_b64_tr_b16 v[104:105], v186 offset:30208
	s_waitcnt lgkmcnt(12)
	v_mfma_f32_32x32x16_bf16 v[50:65], v[170:173], v[126:129], v[50:65]
	v_add_f32_e32 v106, v112, v122
	v_add_f32_e32 v106, v113, v106
	v_add_f32_e32 v106, v82, v106
	v_add_f32_e32 v122, v83, v106
	v_cvt_pk_bf16_f32 v136, v110, v111
	v_cvt_pk_bf16_f32 v137, v112, v113
	ds_read_b64_tr_b16 v[106:107], v186 offset:26624
	ds_read_b64_tr_b16 v[108:109], v186 offset:27136
	s_waitcnt lgkmcnt(13)
	v_mfma_f32_32x32x16_bf16 v[66:81], v[166:169], v[118:121], v[66:81]
	v_add_f32_e32 v110, v84, v122
	v_add_f32_e32 v110, v85, v110
	v_add_f32_e32 v110, v86, v110
	v_add_f32_e32 v110, v87, v110
	v_cvt_pk_bf16_f32 v130, v82, v83
	v_cvt_pk_bf16_f32 v131, v84, v85
	ds_read_b64_tr_b16 v[82:83], v186 offset:30720
	ds_read_b64_tr_b16 v[84:85], v186 offset:31232
	s_waitcnt lgkmcnt(14)
	v_mfma_f32_32x32x16_bf16 v[50:65], v[162:165], v[118:121], v[50:65]
	v_add_f32_e32 v110, v88, v110
	v_add_f32_e32 v110, v89, v110
	v_add_f32_e32 v110, v90, v110
	v_add_f32_e32 v110, v91, v110
	v_cvt_pk_bf16_f32 v132, v86, v87
	v_cvt_pk_bf16_f32 v133, v88, v89
	ds_read_b64_tr_b16 v[86:87], v186 offset:27648
	ds_read_b64_tr_b16 v[88:89], v186 offset:28160
	s_waitcnt lgkmcnt(14)
	v_mfma_f32_32x32x16_bf16 v[66:81], v[158:161], v[114:117], v[66:81]
	v_add_f32_e32 v110, v92, v110
	v_add_f32_e32 v110, v93, v110
	v_add_f32_e32 v110, v94, v110
	v_add_f32_e32 v110, v95, v110
	v_cvt_pk_bf16_f32 v122, v90, v91
	v_cvt_pk_bf16_f32 v123, v92, v93
	ds_read_b64_tr_b16 v[90:91], v186 offset:31744
	ds_read_b64_tr_b16 v[92:93], v186 offset:32256
	v_mfma_f32_32x32x16_bf16 v[50:65], v[154:157], v[114:117], v[50:65]
	v_add_f32_e32 v110, v96, v110
	v_add_f32_e32 v110, v97, v110
	v_cvt_pk_bf16_f32 v124, v94, v95
	v_cvt_pk_bf16_f32 v125, v96, v97
	s_add_i32 s8, s18, s40
	s_mov_b32 m0, s8
	s_nop 0
	global_load_lds_dwordx4 v[184:185], off
	s_add_i32 s8, s44, s41
	s_mov_b32 m0, s8
	s_nop 0
	global_load_lds_dwordx4 v[182:183], off
	v_add_f32_e32 v208, v0, v110
	v_max_f32_e32 v94, v66, v67
	v_max3_f32 v95, v68, v69, v51
	v_max3_f32 v94, v94, v50, v52
	v_max3_f32 v94, v94, v53, v70
	v_max3_f32 v95, v95, v72, v73
	v_max3_f32 v94, v94, v71, v54
	v_max3_f32 v95, v95, v56, v57
	v_max3_f32 v94, v94, v55, v74
	v_max3_f32 v95, v95, v76, v77
	v_max3_f32 v94, v94, v75, v58
	v_max3_f32 v95, v95, v60, v61
	v_max3_f32 v94, v94, v59, v78
	v_max3_f32 v95, v95, v80, v81
	v_max3_f32 v94, v94, v79, v62
	v_max3_f32 v95, v95, v64, v65
	v_max3_f32 v0, v94, v63, v95
	v_mov_b32_e32 v94, v0
	s_nop 1
	v_permlane32_swap_b32_e32 v0, v94
	v_max_f32_e32 v0, v0, v94
	v_cmp_lt_f32_e32 vcc, s91, v0
	s_cmp_lg_u64 vcc, 0
	s_cselect_b64 s[8:9], -1, 0
	s_cbranch_vccnz .LBB0_209
